# final output stores with sc0 sc1 nt instead of nt
# speedup vs baseline: 1.0081x; 1.0017x over previous
.LBB0_1508:
	v_lshl_add_u32 v144, s28, 8, v146
	v_lshl_or_b32 v142, s53, 8, v148
	v_ashrrev_i32_e32 v145, 31, v144
	v_ashrrev_i32_e32 v143, 31, v142
	v_lshlrev_b64 v[140:141], 11, v[144:145]
	v_lshl_add_u64 v[140:141], v[140:141], 0, v[142:143]
	v_lshl_add_u64 v[152:153], v[140:141], 1, s[4:5]
	global_load_dwordx2 v[154:155], v[152:153], off
	v_lshl_add_u64 v[156:157], v[140:141], 2, s[82:83]
	s_andn2_b64 vcc, exec, s[0:1]
	s_mov_b64 s[0:1], -1
	s_waitcnt vmcnt(0)
	v_lshlrev_b32_e32 v158, 16, v154
	v_and_b32_e32 v159, 0xffff0000, v154
	v_lshlrev_b32_e32 v154, 16, v155
	v_and_b32_e32 v155, 0xffff0000, v155
	v_pk_add_f32 v[126:127], v[126:127], v[154:155]
	v_pk_add_f32 v[124:125], v[124:125], v[158:159]
	global_store_dwordx4 v[156:157], v[124:127], off sc0 sc1 nt
	global_load_dwordx2 v[124:125], v[152:153], off offset:32
	s_waitcnt vmcnt(0)
	v_lshlrev_b32_e32 v126, 16, v124
	v_and_b32_e32 v127, 0xffff0000, v124
	v_lshlrev_b32_e32 v124, 16, v125
	v_and_b32_e32 v125, 0xffff0000, v125
	v_pk_add_f32 v[122:123], v[122:123], v[124:125]
	v_pk_add_f32 v[120:121], v[120:121], v[126:127]
	global_store_dwordx4 v[156:157], v[120:123], off offset:64 sc0 sc1 nt
	global_load_dwordx2 v[120:121], v[152:153], off offset:256
	s_waitcnt vmcnt(0)
	v_lshlrev_b32_e32 v122, 16, v120
	v_and_b32_e32 v123, 0xffff0000, v120
	v_lshlrev_b32_e32 v120, 16, v121
	v_and_b32_e32 v121, 0xffff0000, v121
	v_pk_add_f32 v[118:119], v[118:119], v[120:121]
	v_pk_add_f32 v[116:117], v[116:117], v[122:123]
	global_store_dwordx4 v[156:157], v[116:119], off offset:512 sc0 sc1 nt
	global_load_dwordx2 v[116:117], v[152:153], off offset:288
	s_waitcnt vmcnt(0)
	v_lshlrev_b32_e32 v122, 16, v116
	v_or_b32_e32 v118, 16, v144
	v_ashrrev_i32_e32 v119, 31, v118
	v_lshlrev_b64 v[118:119], 11, v[118:119]
	v_and_b32_e32 v123, 0xffff0000, v116
	v_lshlrev_b32_e32 v116, 16, v117
	v_and_b32_e32 v117, 0xffff0000, v117
	v_lshl_add_u64 v[118:119], v[118:119], 0, v[142:143]
	v_pk_add_f32 v[110:111], v[110:111], v[116:117]
	v_pk_add_f32 v[108:109], v[108:109], v[122:123]
	v_lshl_add_u64 v[120:121], v[118:119], 1, s[4:5]
	global_store_dwordx4 v[156:157], v[108:111], off offset:576 sc0 sc1 nt
	global_load_dwordx2 v[108:109], v[120:121], off
	v_lshl_add_u64 v[116:117], v[118:119], 2, s[82:83]
	s_waitcnt vmcnt(0)
	v_lshlrev_b32_e32 v118, 16, v108
	v_and_b32_e32 v119, 0xffff0000, v108
	v_lshlrev_b32_e32 v108, 16, v109
	v_and_b32_e32 v109, 0xffff0000, v109
	v_pk_add_f32 v[110:111], v[114:115], v[108:109]
	v_pk_add_f32 v[108:109], v[112:113], v[118:119]
	global_store_dwordx4 v[116:117], v[108:111], off sc0 sc1 nt
	global_load_dwordx2 v[108:109], v[120:121], off offset:32
	s_waitcnt vmcnt(0)
	v_lshlrev_b32_e32 v110, 16, v108
	v_and_b32_e32 v111, 0xffff0000, v108
	v_lshlrev_b32_e32 v108, 16, v109
	v_and_b32_e32 v109, 0xffff0000, v109
	v_pk_add_f32 v[106:107], v[106:107], v[108:109]
	v_pk_add_f32 v[104:105], v[104:105], v[110:111]
	global_store_dwordx4 v[116:117], v[104:107], off offset:64 sc0 sc1 nt
	global_load_dwordx2 v[104:105], v[120:121], off offset:256
	s_waitcnt vmcnt(0)
	v_lshlrev_b32_e32 v106, 16, v104
	v_and_b32_e32 v107, 0xffff0000, v104
	v_lshlrev_b32_e32 v104, 16, v105
	v_and_b32_e32 v105, 0xffff0000, v105
	v_pk_add_f32 v[102:103], v[102:103], v[104:105]
	v_pk_add_f32 v[100:101], v[100:101], v[106:107]
	global_store_dwordx4 v[116:117], v[100:103], off offset:512 sc0 sc1 nt
	global_load_dwordx2 v[100:101], v[120:121], off offset:288
	s_waitcnt vmcnt(0)
	v_lshlrev_b32_e32 v106, 16, v100
	v_or_b32_e32 v102, 32, v144
	v_ashrrev_i32_e32 v103, 31, v102
	v_lshlrev_b64 v[102:103], 11, v[102:103]
	v_and_b32_e32 v107, 0xffff0000, v100
	v_lshlrev_b32_e32 v100, 16, v101
	v_and_b32_e32 v101, 0xffff0000, v101
	v_lshl_add_u64 v[102:103], v[102:103], 0, v[142:143]
	v_pk_add_f32 v[94:95], v[94:95], v[100:101]
	v_pk_add_f32 v[92:93], v[92:93], v[106:107]
	v_lshl_add_u64 v[104:105], v[102:103], 1, s[4:5]
	global_store_dwordx4 v[116:117], v[92:95], off offset:576 sc0 sc1 nt
	global_load_dwordx2 v[92:93], v[104:105], off
	v_lshl_add_u64 v[100:101], v[102:103], 2, s[82:83]
	s_waitcnt vmcnt(0)
	v_lshlrev_b32_e32 v102, 16, v92
	v_and_b32_e32 v103, 0xffff0000, v92
	v_lshlrev_b32_e32 v92, 16, v93
	v_and_b32_e32 v93, 0xffff0000, v93
	v_pk_add_f32 v[94:95], v[98:99], v[92:93]
	v_pk_add_f32 v[92:93], v[96:97], v[102:103]
	global_store_dwordx4 v[100:101], v[92:95], off sc0 sc1 nt
	global_load_dwordx2 v[92:93], v[104:105], off offset:32
	s_waitcnt vmcnt(0)
	v_lshlrev_b32_e32 v94, 16, v92
	v_and_b32_e32 v95, 0xffff0000, v92
	v_lshlrev_b32_e32 v92, 16, v93
	v_and_b32_e32 v93, 0xffff0000, v93
	v_pk_add_f32 v[90:91], v[90:91], v[92:93]
	v_pk_add_f32 v[88:89], v[88:89], v[94:95]
	global_store_dwordx4 v[100:101], v[88:91], off offset:64 sc0 sc1 nt
	global_load_dwordx2 v[88:89], v[104:105], off offset:256
	s_waitcnt vmcnt(0)
	v_lshlrev_b32_e32 v90, 16, v88
	v_and_b32_e32 v91, 0xffff0000, v88
	v_lshlrev_b32_e32 v88, 16, v89
	v_and_b32_e32 v89, 0xffff0000, v89
	v_pk_add_f32 v[86:87], v[86:87], v[88:89]
	v_pk_add_f32 v[84:85], v[84:85], v[90:91]
	global_store_dwordx4 v[100:101], v[84:87], off offset:512 sc0 sc1 nt
	global_load_dwordx2 v[84:85], v[104:105], off offset:288
	s_waitcnt vmcnt(0)
	v_lshlrev_b32_e32 v90, 16, v84
	v_or_b32_e32 v86, 48, v144
	v_ashrrev_i32_e32 v87, 31, v86
	v_lshlrev_b64 v[86:87], 11, v[86:87]
	v_and_b32_e32 v91, 0xffff0000, v84
	v_lshlrev_b32_e32 v84, 16, v85
	v_and_b32_e32 v85, 0xffff0000, v85
	v_lshl_add_u64 v[86:87], v[86:87], 0, v[142:143]
	v_pk_add_f32 v[78:79], v[78:79], v[84:85]
	v_pk_add_f32 v[76:77], v[76:77], v[90:91]
	v_lshl_add_u64 v[88:89], v[86:87], 1, s[4:5]
	global_store_dwordx4 v[100:101], v[76:79], off offset:576 sc0 sc1 nt
	global_load_dwordx2 v[76:77], v[88:89], off
	v_lshl_add_u64 v[84:85], v[86:87], 2, s[82:83]
	s_waitcnt vmcnt(0)
	v_lshlrev_b32_e32 v86, 16, v76
	v_and_b32_e32 v87, 0xffff0000, v76
	v_lshlrev_b32_e32 v76, 16, v77
	v_and_b32_e32 v77, 0xffff0000, v77
	v_pk_add_f32 v[78:79], v[82:83], v[76:77]
	v_pk_add_f32 v[76:77], v[80:81], v[86:87]
	global_store_dwordx4 v[84:85], v[76:79], off sc0 sc1 nt
	global_load_dwordx2 v[76:77], v[88:89], off offset:32
	s_waitcnt vmcnt(0)
	v_lshlrev_b32_e32 v78, 16, v76
	v_and_b32_e32 v79, 0xffff0000, v76
	v_lshlrev_b32_e32 v76, 16, v77
	v_and_b32_e32 v77, 0xffff0000, v77
	v_pk_add_f32 v[74:75], v[74:75], v[76:77]
	v_pk_add_f32 v[72:73], v[72:73], v[78:79]
	global_store_dwordx4 v[84:85], v[72:75], off offset:64 sc0 sc1 nt
	global_load_dwordx2 v[72:73], v[88:89], off offset:256
	s_waitcnt vmcnt(0)
	v_lshlrev_b32_e32 v74, 16, v72
	v_and_b32_e32 v75, 0xffff0000, v72
	v_lshlrev_b32_e32 v72, 16, v73
	v_and_b32_e32 v73, 0xffff0000, v73
	v_pk_add_f32 v[70:71], v[70:71], v[72:73]
	v_pk_add_f32 v[68:69], v[68:69], v[74:75]
	global_store_dwordx4 v[84:85], v[68:71], off offset:512 sc0 sc1 nt
	global_load_dwordx2 v[68:69], v[88:89], off offset:288
	s_waitcnt vmcnt(0)
	v_lshlrev_b32_e32 v74, 16, v68
	v_and_b32_e32 v75, 0xffff0000, v68
	v_lshlrev_b32_e32 v68, 16, v69
	v_and_b32_e32 v69, 0xffff0000, v69
	v_lshl_add_u64 v[70:71], v[140:141], 0, s[10:11]
	v_pk_add_f32 v[66:67], v[66:67], v[68:69]
	v_pk_add_f32 v[64:65], v[64:65], v[74:75]
	v_lshl_add_u64 v[72:73], v[70:71], 1, s[4:5]
	global_store_dwordx4 v[84:85], v[64:67], off offset:576 sc0 sc1 nt
	global_load_dwordx2 v[64:65], v[72:73], off
	s_waitcnt vmcnt(0)
	v_lshlrev_b32_e32 v68, 16, v64
	v_and_b32_e32 v69, 0xffff0000, v64
	v_lshlrev_b32_e32 v64, 16, v65
	v_and_b32_e32 v65, 0xffff0000, v65
	v_lshl_add_u64 v[66:67], v[70:71], 2, s[82:83]
	v_pk_add_f32 v[62:63], v[62:63], v[64:65]
	v_pk_add_f32 v[60:61], v[60:61], v[68:69]
	global_store_dwordx4 v[66:67], v[60:63], off sc0 sc1 nt
	global_load_dwordx2 v[60:61], v[72:73], off offset:32
	s_waitcnt vmcnt(0)
	v_lshlrev_b32_e32 v62, 16, v60
	v_and_b32_e32 v63, 0xffff0000, v60
	v_lshlrev_b32_e32 v60, 16, v61
	v_and_b32_e32 v61, 0xffff0000, v61
	v_pk_add_f32 v[58:59], v[58:59], v[60:61]
	v_pk_add_f32 v[56:57], v[56:57], v[62:63]
	global_store_dwordx4 v[66:67], v[56:59], off offset:64 sc0 sc1 nt
	global_load_dwordx2 v[56:57], v[72:73], off offset:256
	s_waitcnt vmcnt(0)
	v_lshlrev_b32_e32 v58, 16, v56
	v_and_b32_e32 v59, 0xffff0000, v56
	v_lshlrev_b32_e32 v56, 16, v57
	v_and_b32_e32 v57, 0xffff0000, v57
	v_pk_add_f32 v[54:55], v[54:55], v[56:57]
	v_pk_add_f32 v[52:53], v[52:53], v[58:59]
	global_store_dwordx4 v[66:67], v[52:55], off offset:512 sc0 sc1 nt
	global_load_dwordx2 v[52:53], v[72:73], off offset:288
	s_waitcnt vmcnt(0)
	v_lshlrev_b32_e32 v58, 16, v52
	v_and_b32_e32 v59, 0xffff0000, v52
	v_lshlrev_b32_e32 v52, 16, v53
	v_and_b32_e32 v53, 0xffff0000, v53
	v_lshl_add_u64 v[54:55], v[140:141], 0, s[12:13]
	v_pk_add_f32 v[46:47], v[46:47], v[52:53]
	v_pk_add_f32 v[44:45], v[44:45], v[58:59]
	v_lshl_add_u64 v[56:57], v[54:55], 1, s[4:5]
	global_store_dwordx4 v[66:67], v[44:47], off offset:576 sc0 sc1 nt
	global_load_dwordx2 v[44:45], v[56:57], off
	v_lshl_add_u64 v[52:53], v[54:55], 2, s[82:83]
	s_waitcnt vmcnt(0)
	v_lshlrev_b32_e32 v54, 16, v44
	v_and_b32_e32 v55, 0xffff0000, v44
	v_lshlrev_b32_e32 v44, 16, v45
	v_and_b32_e32 v45, 0xffff0000, v45
	v_pk_add_f32 v[46:47], v[50:51], v[44:45]
	v_pk_add_f32 v[44:45], v[48:49], v[54:55]
	global_store_dwordx4 v[52:53], v[44:47], off sc0 sc1 nt
	global_load_dwordx2 v[44:45], v[56:57], off offset:32
	s_waitcnt vmcnt(0)
	v_lshlrev_b32_e32 v46, 16, v44
	v_and_b32_e32 v47, 0xffff0000, v44
	v_lshlrev_b32_e32 v44, 16, v45
	v_and_b32_e32 v45, 0xffff0000, v45
	v_pk_add_f32 v[42:43], v[42:43], v[44:45]
	v_pk_add_f32 v[40:41], v[40:41], v[46:47]
	global_store_dwordx4 v[52:53], v[40:43], off offset:64 sc0 sc1 nt
	global_load_dwordx2 v[40:41], v[56:57], off offset:256
	s_waitcnt vmcnt(0)
	v_lshlrev_b32_e32 v42, 16, v40
	v_and_b32_e32 v43, 0xffff0000, v40
	v_lshlrev_b32_e32 v40, 16, v41
	v_and_b32_e32 v41, 0xffff0000, v41
	v_pk_add_f32 v[38:39], v[38:39], v[40:41]
	v_pk_add_f32 v[36:37], v[36:37], v[42:43]
	global_store_dwordx4 v[52:53], v[36:39], off offset:512 sc0 sc1 nt
	global_load_dwordx2 v[36:37], v[56:57], off offset:288
	s_waitcnt vmcnt(0)
	v_lshlrev_b32_e32 v42, 16, v36
	v_and_b32_e32 v43, 0xffff0000, v36
	v_lshlrev_b32_e32 v36, 16, v37
	v_and_b32_e32 v37, 0xffff0000, v37
	v_lshl_add_u64 v[38:39], v[140:141], 0, s[14:15]
	v_pk_add_f32 v[30:31], v[30:31], v[36:37]
	v_pk_add_f32 v[28:29], v[28:29], v[42:43]
	v_lshl_add_u64 v[40:41], v[38:39], 1, s[4:5]
	global_store_dwordx4 v[52:53], v[28:31], off offset:576 sc0 sc1 nt
	global_load_dwordx2 v[28:29], v[40:41], off
	v_lshl_add_u64 v[36:37], v[38:39], 2, s[82:83]
	s_waitcnt vmcnt(0)
	v_lshlrev_b32_e32 v38, 16, v28
	v_and_b32_e32 v39, 0xffff0000, v28
	v_lshlrev_b32_e32 v28, 16, v29
	v_and_b32_e32 v29, 0xffff0000, v29
	v_pk_add_f32 v[30:31], v[34:35], v[28:29]
	v_pk_add_f32 v[28:29], v[32:33], v[38:39]
	global_store_dwordx4 v[36:37], v[28:31], off sc0 sc1 nt
	global_load_dwordx2 v[28:29], v[40:41], off offset:32
	s_waitcnt vmcnt(0)
	v_lshlrev_b32_e32 v30, 16, v28
	v_and_b32_e32 v31, 0xffff0000, v28
	v_lshlrev_b32_e32 v28, 16, v29
	v_and_b32_e32 v29, 0xffff0000, v29
	v_pk_add_f32 v[26:27], v[26:27], v[28:29]
	v_pk_add_f32 v[24:25], v[24:25], v[30:31]
	global_store_dwordx4 v[36:37], v[24:27], off offset:64 sc0 sc1 nt
	global_load_dwordx2 v[24:25], v[40:41], off offset:256
	s_waitcnt vmcnt(0)
	v_lshlrev_b32_e32 v26, 16, v24
	v_and_b32_e32 v27, 0xffff0000, v24
	v_lshlrev_b32_e32 v24, 16, v25
	v_and_b32_e32 v25, 0xffff0000, v25
	v_pk_add_f32 v[22:23], v[22:23], v[24:25]
	v_pk_add_f32 v[20:21], v[20:21], v[26:27]
	global_store_dwordx4 v[36:37], v[20:23], off offset:512 sc0 sc1 nt
	global_load_dwordx2 v[20:21], v[40:41], off offset:288
	s_waitcnt vmcnt(0)
	v_lshlrev_b32_e32 v26, 16, v20
	v_and_b32_e32 v27, 0xffff0000, v20
	v_lshlrev_b32_e32 v20, 16, v21
	v_and_b32_e32 v21, 0xffff0000, v21
	v_lshl_add_u64 v[22:23], v[140:141], 0, s[16:17]
	v_pk_add_f32 v[14:15], v[14:15], v[20:21]
	v_pk_add_f32 v[12:13], v[12:13], v[26:27]
	v_lshl_add_u64 v[24:25], v[22:23], 1, s[4:5]
	global_store_dwordx4 v[36:37], v[12:15], off offset:576 sc0 sc1 nt
	global_load_dwordx2 v[12:13], v[24:25], off
	v_lshl_add_u64 v[20:21], v[22:23], 2, s[82:83]
	s_waitcnt vmcnt(0)
	v_lshlrev_b32_e32 v22, 16, v12
	v_and_b32_e32 v23, 0xffff0000, v12
	v_lshlrev_b32_e32 v12, 16, v13
	v_and_b32_e32 v13, 0xffff0000, v13
	v_pk_add_f32 v[14:15], v[18:19], v[12:13]
	v_pk_add_f32 v[12:13], v[16:17], v[22:23]
	global_store_dwordx4 v[20:21], v[12:15], off sc0 sc1 nt
	global_load_dwordx2 v[12:13], v[24:25], off offset:32
	s_waitcnt vmcnt(0)
	v_lshlrev_b32_e32 v14, 16, v12
	v_and_b32_e32 v15, 0xffff0000, v12
	v_lshlrev_b32_e32 v12, 16, v13
	v_and_b32_e32 v13, 0xffff0000, v13
	v_pk_add_f32 v[10:11], v[10:11], v[12:13]
	v_pk_add_f32 v[8:9], v[8:9], v[14:15]
	global_store_dwordx4 v[20:21], v[8:11], off offset:64 sc0 sc1 nt
	global_load_dwordx2 v[8:9], v[24:25], off offset:256
	s_waitcnt vmcnt(0)
	v_lshlrev_b32_e32 v10, 16, v8
	v_and_b32_e32 v11, 0xffff0000, v8
	v_lshlrev_b32_e32 v8, 16, v9
	v_and_b32_e32 v9, 0xffff0000, v9
	v_pk_add_f32 v[6:7], v[6:7], v[8:9]
	v_pk_add_f32 v[4:5], v[4:5], v[10:11]
	global_store_dwordx4 v[20:21], v[4:7], off offset:512 sc0 sc1 nt
	global_load_dwordx2 v[4:5], v[24:25], off offset:288
	s_waitcnt vmcnt(0)
	v_lshlrev_b32_e32 v6, 16, v4
	v_and_b32_e32 v7, 0xffff0000, v4
	v_lshlrev_b32_e32 v4, 16, v5
	v_and_b32_e32 v5, 0xffff0000, v5
	v_pk_add_f32 v[2:3], v[2:3], v[4:5]
	v_pk_add_f32 v[0:1], v[0:1], v[6:7]
	global_store_dwordx4 v[20:21], v[0:3], off offset:576 sc0 sc1 nt
	s_cbranch_vccnz .LBB0_1497
	s_andn2_b64 vcc, exec, s[2:3]
	s_cbranch_vccnz .LBB0_1496
	s_barrier
	s_branch .LBB0_1496
